# P0 S5 table job: its 15 parameter loads issued in one batch (were five dependent groups), stacked on v85
# baseline (speedup 1.0000x reference)
.LBB0_12:
	s_ashr_i32 s84, s43, 2
	s_lshl_b32 s78, s84, 6
	s_ashr_i32 s79, s78, 31
	v_readlane_b32 s8, v254, 29
	s_lshl_b64 s[4:5], s[78:79], 2
	v_readlane_b32 s18, v254, 39
	v_readlane_b32 s19, v254, 40
	s_add_u32 s36, s18, s4
	v_readlane_b32 s20, v254, 41
	s_addc_u32 s37, s19, s5
	v_readlane_b32 s21, v254, 42
	s_add_u32 s38, s20, s4
	s_addc_u32 s39, s21, s5
	s_ashr_i32 s85, s84, 31
	v_readlane_b32 s22, v254, 43
	s_lshl_b64 s[46:47], s[84:85], 2
	v_readlane_b32 s23, v254, 44
	s_add_u32 s46, s22, s46
	s_addc_u32 s47, s23, s47
	global_load_dword v2, v63, s[46:47]
	global_load_dword v3, v85, s[38:39]
	global_load_dword v6, v85, s[36:37]
	s_lshl_b64 s[98:99], s[84:85], 12
	v_lshl_add_u64 v[232:233], v[64:65], 0, s[98:99]
	v_lshl_add_u64 v[234:235], v[68:69], 0, s[98:99]
	v_lshl_add_u64 v[236:237], v[70:71], 0, s[4:5]
	v_lshl_add_u64 v[238:239], v[72:73], 0, s[4:5]
	global_load_dword v220, v[238:239], off
	global_load_dword v221, v[236:237], off
	global_load_dword v222, v[234:235], off
	global_load_dword v223, v[232:233], off
	v_lshl_add_u64 v[232:233], v[232:233], 0, s[34:35]
	v_lshl_add_u64 v[234:235], v[234:235], 0, s[34:35]
	v_lshl_add_u64 v[236:237], v[236:237], 0, s[72:73]
	v_lshl_add_u64 v[238:239], v[238:239], 0, s[72:73]
	global_load_dword v224, v[238:239], off
	global_load_dword v225, v[236:237], off
	global_load_dword v226, v[234:235], off
	global_load_dword v227, v[232:233], off
	v_lshl_add_u64 v[232:233], v[74:75], 0, s[98:99]
	v_lshl_add_u64 v[234:235], v[76:77], 0, s[98:99]
	global_load_dword v228, v[232:233], off
	global_load_dword v229, v[234:235], off
	v_lshl_add_u64 v[232:233], v[232:233], 0, s[34:35]
	v_lshl_add_u64 v[234:235], v[234:235], 0, s[34:35]
	global_load_dword v230, v[232:233], off
	global_load_dword v231, v[234:235], off
	s_mov_b32 s2, 0x3fb8aa3b
	s_mov_b64 s[36:37], 0
	v_mov_b32_e32 v8, v84
	v_readlane_b32 s9, v254, 30
	v_readlane_b32 s10, v254, 31
	v_readlane_b32 s11, v254, 32
	v_readlane_b32 s12, v254, 33
	v_readlane_b32 s13, v254, 34
	v_readlane_b32 s14, v254, 35
	v_readlane_b32 s15, v254, 36
	v_readlane_b32 s16, v254, 37
	v_readlane_b32 s17, v254, 38
	s_waitcnt vmcnt(2)
	v_mul_f32_e32 v4, 0x3fb8aa3b, v2
	v_fma_f32 v5, v2, s2, -v4
	v_rndne_f32_e32 v7, v4
	v_fmac_f32_e32 v5, 0x32a5705f, v2
	v_sub_f32_e32 v4, v4, v7
	v_add_f32_e32 v4, v4, v5
	v_cvt_i32_f32_e32 v9, v7
	v_exp_f32_e32 v10, v4
	s_mov_b32 s2, 0xc2ce8ed0
	s_waitcnt vmcnt(1)
	v_cvt_f64_f32_e32 v[4:5], v3
	v_cmp_ngt_f32_e32 vcc, s2, v2
	v_ldexp_f32 v3, v10, v9
	s_mov_b32 s2, 0x42b17218
	v_cndmask_b32_e32 v3, 0, v3, vcc
	v_cmp_nlt_f32_e32 vcc, s2, v2
	v_mov_b32_e32 v7, v89
	v_mov_b32_e32 v9, v88
	v_cndmask_b32_e32 v12, v95, v3, vcc
	v_cvt_f64_f32_e32 v[2:3], v12
.LBB0_13:
	v_cvt_f32_u32_e32 v13, v7
	v_cvt_f64_u32_e32 v[10:11], v7
	v_mul_f64 v[10:11], v[2:3], v[10:11]
	v_mul_f64 v[10:11], v[10:11], v[4:5]
	v_mul_f64 v[14:15], v[10:11], s[30:31]
	v_mul_f32_e32 v13, v12, v13
	v_rndne_f64_e32 v[14:15], v[14:15]
	s_waitcnt vmcnt(0)
	v_mul_f32_e32 v13, v6, v13
	v_fma_f64 v[10:11], v[10:11], s[30:31], -v[14:15]
	v_cvt_f32_f64_e32 v11, v[10:11]
	v_mul_f32_e32 v10, 0x3fb8aa3b, v13
	v_exp_f32_e32 v10, v10
	v_cos_f32_e32 v14, v11
	v_sin_f32_e32 v15, v11
	v_add_u32_e32 v9, 0x200, v9
	s_movk_i32 s2, 0x23f
	v_cmp_lt_u32_e32 vcc, s2, v9
	v_pk_mul_f32 v[10:11], v[10:11], v[14:15] op_sel_hi:[0,1]
	v_add_u32_e32 v7, 8, v7
	s_or_b64 s[36:37], vcc, s[36:37]
	ds_write_b64 v8, v[10:11]
	v_add_u32_e32 v8, 0x1000, v8
	s_andn2_b64 exec, exec, s[36:37]
	s_cbranch_execnz .LBB0_13
	s_or_b64 exec, exec, s[36:37]
	s_lshl_b64 s[36:37], s[84:85], 12
	v_lshl_add_u64 v[4:5], v[64:65], 0, s[36:37]
	v_lshl_add_u64 v[6:7], v[68:69], 0, s[36:37]
	v_lshl_add_u64 v[8:9], v[70:71], 0, s[4:5]
	v_lshl_add_u64 v[10:11], v[72:73], 0, s[4:5]
	s_mov_b64 s[4:5], 0
	v_mov_b32_e32 v13, v88
	v_mov_b32_e32 v14, v90
	s_waitcnt vmcnt(0)
.LBB0_15:
	v_mov_b32_e32 v17, v220
	v_mov_b32_e32 v16, v221
	v_mov_b32_e32 v18, v222
	v_mov_b32_e32 v20, v223
	v_lshl_add_u64 v[4:5], v[4:5], 0, s[34:35]
	v_lshl_add_u64 v[6:7], v[6:7], 0, s[34:35]
	v_lshl_add_u64 v[8:9], v[8:9], 0, s[72:73]
	v_lshl_add_u64 v[10:11], v[10:11], 0, s[72:73]
	s_waitcnt vmcnt(3)
	v_cvt_f64_f32_e32 v[24:25], v17
	s_waitcnt vmcnt(2)
	v_mul_f32_e32 v22, v12, v16
	v_pk_mul_f32 v[26:27], v[16:17], v[16:17]
	v_mul_f64 v[24:25], v[2:3], v[24:25]
	v_mov_b32_e32 v28, v17
	v_fmamk_f32 v15, v22, 0x3c088889, v96
	v_add_f32_e32 v17, v26, v27
	v_mul_f64 v[26:27], v[24:25], s[30:31]
	v_fmaak_f32 v15, v22, v15, 0x3e2aaaab
	v_div_scale_f32 v19, s[38:39], v17, v17, 1.0
	v_rndne_f64_e32 v[26:27], v[26:27]
	v_fma_f32 v15, v22, v15, 0.5
	v_rcp_f32_e32 v29, v19
	v_fma_f64 v[24:25], v[24:25], s[30:31], -v[26:27]
	v_fma_f32 v78, v22, v15, 1.0
	v_cvt_f32_f64_e32 v15, v[24:25]
	v_sin_f32_e32 v30, v15
	v_cos_f32_e32 v24, v15
	v_mul_f32_e32 v15, 0.5, v15
	v_sin_f32_e32 v23, v15
	v_fma_f32 v15, -v19, v29, 1.0
	v_div_scale_f32 v21, vcc, 1.0, v17, 1.0
	v_fmac_f32_e32 v29, v15, v29
	v_mul_f32_e32 v15, v21, v29
	v_fma_f32 v31, -v19, v15, v21
	v_pk_mul_f32 v[26:27], v[22:23], v[78:79]
	v_fmac_f32_e32 v15, v31, v29
	v_add_f32_e32 v31, 1.0, v26
	v_mov_b32_e32 v25, v23
	v_mul_f32_e32 v22, v23, v27
	v_mul_f32_e32 v23, v30, v31
	v_pk_fma_f32 v[24:25], v[24:25], v[26:27], v[22:23] op_sel_hi:[1,1,0] neg_lo:[0,0,1] neg_hi:[0,0,1]
	v_fma_f32 v19, -v19, v15, v21
	v_mov_b32_e32 v22, v24
	v_div_fmas_f32 v15, v19, v29, v15
	v_pk_mul_f32 v[28:29], v[28:29], v[22:23] op_sel:[0,1] op_sel_hi:[0,0]
	v_div_fixup_f32 v26, v15, v17, 1.0
	v_pk_fma_f32 v[24:25], v[16:17], v[24:25], v[28:29]
	v_pk_fma_f32 v[16:17], v[16:17], v[22:23], v[28:29] op_sel_hi:[0,1,1] neg_lo:[0,0,1] neg_hi:[0,0,1]
	v_mov_b32_e32 v25, v17
	v_pk_mul_f32 v[16:17], v[26:27], v[24:25] op_sel_hi:[0,1]
	v_add_co_u32_e32 v13, vcc, 0x200, v13
	s_waitcnt vmcnt(1)
	v_pk_mul_f32 v[18:19], v[18:19], v[16:17] op_sel:[0,1] op_sel_hi:[0,0]
	s_xor_b64 s[38:39], vcc, -1
	s_waitcnt vmcnt(0)
	v_pk_fma_f32 v[22:23], v[20:21], v[16:17], v[18:19] neg_lo:[0,0,1] neg_hi:[0,0,1]
	v_pk_fma_f32 v[16:17], v[20:21], v[16:17], v[18:19] op_sel_hi:[0,1,1]
	s_and_b64 s[38:39], exec, s[38:39]
	v_mov_b32_e32 v23, v17
	s_or_b64 s[4:5], s[38:39], s[4:5]
	ds_write_b64 v14, v[22:23]
	v_add_u32_e32 v14, 0x1000, v14
	v_mov_b32_e32 v220, v224
	v_mov_b32_e32 v221, v225
	v_mov_b32_e32 v222, v226
	v_mov_b32_e32 v223, v227
	s_andn2_b64 exec, exec, s[4:5]
	s_cbranch_execnz .LBB0_15
	s_or_b64 exec, exec, s[4:5]
	v_lshl_add_u64 v[2:3], v[74:75], 0, s[36:37]
	v_lshl_add_u64 v[4:5], v[76:77], 0, s[36:37]
	s_mov_b64 s[4:5], 0
	v_mov_b32_e32 v6, v88
	v_mov_b32_e32 v7, v91
.LBB0_17:
	v_mov_b32_e32 v8, v228
	v_mov_b32_e32 v9, v229
	v_add_co_u32_e32 v6, vcc, 0x200, v6
	s_xor_b64 s[36:37], vcc, -1
	s_and_b64 s[36:37], exec, s[36:37]
	v_lshl_add_u64 v[2:3], v[2:3], 0, s[34:35]
	v_lshl_add_u64 v[4:5], v[4:5], 0, s[34:35]
	s_or_b64 s[4:5], s[36:37], s[4:5]
	s_waitcnt vmcnt(0)
	ds_write_b64 v7, v[8:9]
	v_add_u32_e32 v7, 0x1000, v7
	v_mov_b32_e32 v228, v230
	v_mov_b32_e32 v229, v231
	s_andn2_b64 exec, exec, s[4:5]
	s_cbranch_execnz .LBB0_17
	s_or_b64 exec, exec, s[4:5]
	s_and_b32 s2, s42, 3
	v_lshl_or_b32 v6, s2, 10, v0
	v_lshrrev_b32_e32 v9, 2, v6
	v_lshlrev_b32_e32 v3, 1, v0
	v_and_or_b32 v2, v9, 48, v1
	v_and_b32_e32 v3, 64, v3
	s_and_b32 s46, s43, 3
	v_sub_u32_e32 v2, v2, v3
	v_and_b32_e32 v3, 0x300, v9
	v_sub_u32_e32 v2, v2, v3
	s_lshl_b32 s47, s46, 10
	s_lshl_b64 s[4:5], s[84:85], 16
	v_lshrrev_b16_e32 v7, 1, v6
	v_lshl_add_u32 v10, v2, 3, s3
	v_or_b32_e32 v62, s47, v0
	v_lshl_or_b32 v2, v6, 4, s4
	v_mov_b32_e32 v3, s5
	v_lshrrev_b32_e32 v8, 5, v6
	s_addk_i32 s47, 0x400
	v_lshl_add_u64 v[4:5], s[26:27], 0, v[2:3]
	s_mov_b64 s[4:5], 0
	v_mov_b32_e32 v11, v7
	v_mov_b32_e32 v12, v62
	s_waitcnt lgkmcnt(0)
	s_barrier

.LBB0_121:
	s_ashr_i32 s36, s43, 2
	s_lshl_b32 s34, s36, 6
	s_ashr_i32 s35, s34, 31
	v_readlane_b32 s72, v254, 29
	s_lshl_b64 s[4:5], s[34:35], 2
	v_readlane_b32 s82, v254, 39
	v_readlane_b32 s83, v254, 40
	s_add_u32 s38, s82, s4
	v_readlane_b32 s84, v254, 41
	s_addc_u32 s39, s83, s5
	v_readlane_b32 s85, v254, 42
	s_add_u32 s46, s84, s4
	s_addc_u32 s47, s85, s5
	s_ashr_i32 s37, s36, 31
	v_readlane_b32 s86, v254, 43
	s_lshl_b64 s[48:49], s[36:37], 2
	v_readlane_b32 s87, v254, 44
	s_add_u32 s48, s86, s48
	s_addc_u32 s49, s87, s49
	global_load_dword v2, v63, s[48:49]
	global_load_dword v3, v85, s[46:47]
	global_load_dword v6, v85, s[38:39]
	s_lshl_b64 s[98:99], s[36:37], 12
	v_lshl_add_u64 v[232:233], v[64:65], 0, s[98:99]
	v_lshl_add_u64 v[234:235], v[68:69], 0, s[98:99]
	v_lshl_add_u64 v[236:237], v[70:71], 0, s[4:5]
	v_lshl_add_u64 v[238:239], v[72:73], 0, s[4:5]
	global_load_dword v220, v[238:239], off
	global_load_dword v221, v[236:237], off
	global_load_dword v222, v[234:235], off
	global_load_dword v223, v[232:233], off
	v_lshl_add_u64 v[232:233], v[232:233], 0, s[26:27]
	v_lshl_add_u64 v[234:235], v[234:235], 0, s[26:27]
	v_lshl_add_u64 v[236:237], v[236:237], 0, s[28:29]
	v_lshl_add_u64 v[238:239], v[238:239], 0, s[28:29]
	global_load_dword v224, v[238:239], off
	global_load_dword v225, v[236:237], off
	global_load_dword v226, v[234:235], off
	global_load_dword v227, v[232:233], off
	v_lshl_add_u64 v[232:233], v[74:75], 0, s[98:99]
	v_lshl_add_u64 v[234:235], v[76:77], 0, s[98:99]
	global_load_dword v228, v[232:233], off
	global_load_dword v229, v[234:235], off
	v_lshl_add_u64 v[232:233], v[232:233], 0, s[26:27]
	v_lshl_add_u64 v[234:235], v[234:235], 0, s[26:27]
	global_load_dword v230, v[232:233], off
	global_load_dword v231, v[234:235], off
	s_mov_b32 s2, 0x3fb8aa3b
	s_mov_b64 s[38:39], 0
	s_waitcnt vmcnt(7)
	v_mov_b32_e32 v8, v89
	v_readlane_b32 s73, v254, 30
	v_readlane_b32 s74, v254, 31
	v_readlane_b32 s75, v254, 32
	v_readlane_b32 s76, v254, 33
	v_readlane_b32 s77, v254, 34
	v_readlane_b32 s78, v254, 35
	v_readlane_b32 s79, v254, 36
	v_readlane_b32 s80, v254, 37
	v_readlane_b32 s81, v254, 38
	s_waitcnt vmcnt(2)
	v_mul_f32_e32 v4, 0x3fb8aa3b, v2
	v_fma_f32 v5, v2, s2, -v4
	v_rndne_f32_e32 v7, v4
	v_fmac_f32_e32 v5, 0x32a5705f, v2
	v_sub_f32_e32 v4, v4, v7
	v_add_f32_e32 v4, v4, v5
	v_cvt_i32_f32_e32 v9, v7
	v_exp_f32_e32 v10, v4
	s_mov_b32 s2, 0xc2ce8ed0
	s_waitcnt vmcnt(1)
	v_cvt_f64_f32_e32 v[4:5], v3
	v_cmp_ngt_f32_e32 vcc, s2, v2
	v_ldexp_f32 v3, v10, v9
	s_mov_b32 s2, 0x42b17218
	v_cndmask_b32_e32 v3, 0, v3, vcc
	v_cmp_nlt_f32_e32 vcc, s2, v2
	v_mov_b32_e32 v7, v90
	v_mov_b32_e32 v9, v88
	v_cndmask_b32_e32 v12, v94, v3, vcc
	v_cvt_f64_f32_e32 v[2:3], v12
.LBB0_122:
	v_cvt_f32_u32_e32 v13, v7
	v_cvt_f64_u32_e32 v[10:11], v7
	v_mul_f64 v[10:11], v[2:3], v[10:11]
	v_mul_f64 v[10:11], v[10:11], v[4:5]
	v_mul_f64 v[14:15], v[10:11], s[24:25]
	v_mul_f32_e32 v13, v12, v13
	v_rndne_f64_e32 v[14:15], v[14:15]
	s_waitcnt vmcnt(0)
	v_mul_f32_e32 v13, v6, v13
	v_fma_f64 v[10:11], v[10:11], s[24:25], -v[14:15]
	v_cvt_f32_f64_e32 v11, v[10:11]
	v_mul_f32_e32 v10, 0x3fb8aa3b, v13
	v_exp_f32_e32 v10, v10
	v_cos_f32_e32 v14, v11
	v_sin_f32_e32 v15, v11
	v_add_u32_e32 v9, 0x200, v9
	s_movk_i32 s2, 0x23f
	v_cmp_lt_u32_e32 vcc, s2, v9
	v_pk_mul_f32 v[10:11], v[10:11], v[14:15] op_sel_hi:[0,1]
	v_add_u32_e32 v7, 8, v7
	s_or_b64 s[38:39], vcc, s[38:39]
	ds_write_b64 v8, v[10:11]
	v_add_u32_e32 v8, 0x1000, v8
	s_andn2_b64 exec, exec, s[38:39]
	s_cbranch_execnz .LBB0_122
	s_or_b64 exec, exec, s[38:39]
	s_lshl_b64 s[38:39], s[36:37], 12
	v_lshl_add_u64 v[4:5], v[64:65], 0, s[38:39]
	v_lshl_add_u64 v[6:7], v[68:69], 0, s[38:39]
	v_lshl_add_u64 v[8:9], v[70:71], 0, s[4:5]
	v_lshl_add_u64 v[10:11], v[72:73], 0, s[4:5]
	s_mov_b64 s[4:5], 0
	v_mov_b32_e32 v13, v88
	v_mov_b32_e32 v14, v91
	s_waitcnt vmcnt(0)
.LBB0_124:
	v_mov_b32_e32 v17, v220
	v_mov_b32_e32 v16, v221
	v_mov_b32_e32 v18, v222
	v_mov_b32_e32 v20, v223
	v_lshl_add_u64 v[4:5], v[4:5], 0, s[26:27]
	v_lshl_add_u64 v[6:7], v[6:7], 0, s[26:27]
	v_lshl_add_u64 v[8:9], v[8:9], 0, s[28:29]
	v_lshl_add_u64 v[10:11], v[10:11], 0, s[28:29]
	s_waitcnt vmcnt(3)
	v_cvt_f64_f32_e32 v[24:25], v17
	s_waitcnt vmcnt(2)
	v_mul_f32_e32 v22, v12, v16
	v_pk_mul_f32 v[26:27], v[16:17], v[16:17]
	v_mul_f64 v[24:25], v[2:3], v[24:25]
	v_mov_b32_e32 v28, v17
	v_fmamk_f32 v15, v22, 0x3c088889, v95
	v_add_f32_e32 v17, v26, v27
	v_mul_f64 v[26:27], v[24:25], s[24:25]
	v_fmaak_f32 v15, v22, v15, 0x3e2aaaab
	v_div_scale_f32 v19, s[46:47], v17, v17, 1.0
	v_rndne_f64_e32 v[26:27], v[26:27]
	v_fma_f32 v15, v22, v15, 0.5
	v_rcp_f32_e32 v29, v19
	v_fma_f64 v[24:25], v[24:25], s[24:25], -v[26:27]
	v_fma_f32 v78, v22, v15, 1.0
	v_cvt_f32_f64_e32 v15, v[24:25]
	v_sin_f32_e32 v30, v15
	v_cos_f32_e32 v24, v15
	v_mul_f32_e32 v15, 0.5, v15
	v_sin_f32_e32 v23, v15
	v_fma_f32 v15, -v19, v29, 1.0
	v_div_scale_f32 v21, vcc, 1.0, v17, 1.0
	v_fmac_f32_e32 v29, v15, v29
	v_mul_f32_e32 v15, v21, v29
	v_fma_f32 v31, -v19, v15, v21
	v_pk_mul_f32 v[26:27], v[22:23], v[78:79]
	v_fmac_f32_e32 v15, v31, v29
	v_add_f32_e32 v31, 1.0, v26
	v_mov_b32_e32 v25, v23
	v_mul_f32_e32 v22, v23, v27
	v_mul_f32_e32 v23, v30, v31
	v_pk_fma_f32 v[24:25], v[24:25], v[26:27], v[22:23] op_sel_hi:[1,1,0] neg_lo:[0,0,1] neg_hi:[0,0,1]
	v_fma_f32 v19, -v19, v15, v21
	v_mov_b32_e32 v22, v24
	v_div_fmas_f32 v15, v19, v29, v15
	v_pk_mul_f32 v[28:29], v[28:29], v[22:23] op_sel:[0,1] op_sel_hi:[0,0]
	v_div_fixup_f32 v26, v15, v17, 1.0
	v_pk_fma_f32 v[24:25], v[16:17], v[24:25], v[28:29]
	v_pk_fma_f32 v[16:17], v[16:17], v[22:23], v[28:29] op_sel_hi:[0,1,1] neg_lo:[0,0,1] neg_hi:[0,0,1]
	v_mov_b32_e32 v25, v17
	v_pk_mul_f32 v[16:17], v[26:27], v[24:25] op_sel_hi:[0,1]
	v_add_co_u32_e32 v13, vcc, 0x200, v13
	s_waitcnt vmcnt(1)
	v_pk_mul_f32 v[18:19], v[18:19], v[16:17] op_sel:[0,1] op_sel_hi:[0,0]
	s_xor_b64 s[46:47], vcc, -1
	s_waitcnt vmcnt(0)
	v_pk_fma_f32 v[22:23], v[20:21], v[16:17], v[18:19] neg_lo:[0,0,1] neg_hi:[0,0,1]
	v_pk_fma_f32 v[16:17], v[20:21], v[16:17], v[18:19] op_sel_hi:[0,1,1]
	s_and_b64 s[46:47], exec, s[46:47]
	v_mov_b32_e32 v23, v17
	s_or_b64 s[4:5], s[46:47], s[4:5]
	ds_write_b64 v14, v[22:23]
	v_add_u32_e32 v14, 0x1000, v14
	v_mov_b32_e32 v220, v224
	v_mov_b32_e32 v221, v225
	v_mov_b32_e32 v222, v226
	v_mov_b32_e32 v223, v227
	s_andn2_b64 exec, exec, s[4:5]
	s_cbranch_execnz .LBB0_124
	s_or_b64 exec, exec, s[4:5]
	v_lshl_add_u64 v[2:3], v[74:75], 0, s[38:39]
	v_lshl_add_u64 v[4:5], v[76:77], 0, s[38:39]
	s_mov_b64 s[4:5], 0
	v_mov_b32_e32 v6, v88
	v_mov_b32_e32 v7, v92
.LBB0_126:
	v_mov_b32_e32 v8, v228
	v_mov_b32_e32 v9, v229
	v_add_co_u32_e32 v6, vcc, 0x200, v6
	s_xor_b64 s[38:39], vcc, -1
	s_and_b64 s[38:39], exec, s[38:39]
	v_lshl_add_u64 v[2:3], v[2:3], 0, s[26:27]
	v_lshl_add_u64 v[4:5], v[4:5], 0, s[26:27]
	s_or_b64 s[4:5], s[38:39], s[4:5]
	s_waitcnt vmcnt(0)
	ds_write_b64 v7, v[8:9]
	v_add_u32_e32 v7, 0x1000, v7
	v_mov_b32_e32 v228, v230
	v_mov_b32_e32 v229, v231
	s_andn2_b64 exec, exec, s[4:5]
	s_cbranch_execnz .LBB0_126
	s_or_b64 exec, exec, s[4:5]
	s_and_b32 s2, s42, 3
	v_lshl_or_b32 v6, s2, 10, v0
	v_lshrrev_b32_e32 v9, 2, v6
	v_lshlrev_b32_e32 v3, 1, v0
	v_and_or_b32 v2, v9, 48, v1
	v_and_b32_e32 v3, 64, v3
	s_and_b32 s35, s43, 3
	v_sub_u32_e32 v2, v2, v3
	v_and_b32_e32 v3, 0x300, v9
	v_sub_u32_e32 v2, v2, v3
	s_lshl_b32 s46, s35, 10
	s_lshl_b64 s[4:5], s[36:37], 16
	v_lshrrev_b16_e32 v7, 1, v6
	v_lshl_add_u32 v10, v2, 3, s3
	v_or_b32_e32 v62, s46, v0
	v_lshl_or_b32 v2, v6, 4, s4
	v_mov_b32_e32 v3, s5
	v_lshrrev_b32_e32 v8, 5, v6
	s_addk_i32 s46, 0x400
	v_lshl_add_u64 v[4:5], s[8:9], 0, v[2:3]
	s_mov_b64 s[38:39], 0
	v_mov_b32_e32 v11, v7
	v_mov_b32_e32 v12, v62
	s_waitcnt lgkmcnt(0)
	s_barrier
